# LRUC: workgroup->item map by XCD (bid%8 = batch): the 32 WGs of an XCD sweep one batch across all channel blocks
# speedup vs baseline: 1.0238x; 1.0062x over previous
; __device__ __forceinline__ int opaque_bid() { int t; asm volatile("s_mov_b32 %0, %1" : "=s"(t) : "s"((int)blockIdx.x)); return t; }
; template <int DIR>
; __device__ __forceinline__ void lru_dir(const bf16_t* XR, const bf16_t* GATE, bf16_t* YP, u32x4* HSF, const bf16_t* bdw_dir, float bias_r, float bias_i, float sp,
;                                         int b, int n2, int lane, int wave, LAS float* xl) {
;     const int e = lane & 31, hh = lane >> 5, n = n2 >> 1, half = n2 & 1;
;     const int tau = 16 * ((e >> 2) & 1) + (e & 3) + 4 * (e >> 3);
;     bf16x8 Br[4], Bi[4];
;     const bf16_t* wrp = bdw_dir + (size_t)n * 4096 + (half * 32 + e) * 64 + 8 * hh;
;     const bf16_t* wip = wrp + 16 * 4096;
; #pragma unroll
;     for (int kk = 0; kk < 4; ++kk) { Br[kk] = *(const bf16x8*)(wrp + 16 * kk); Bi[kk] = *(const bf16x8*)(wip + 16 * kk); }
;     bf16x8 I0, I1;
; #pragma unroll
;     for (int jj = 0; jj < 8; ++jj) { I0[jj] = (8 * hh + jj == e) ? (short)0x3F80 : (short)0; I1[jj] = (16 + 8 * hh + jj == e) ? (short)0x3F80 : (short)0; }
;     const bool first = (hh == DIR);
;     const int chcol = n * 64 + half * 32;
;     const float spm = -8.0f * 1.4426950408889634f * sp;
; __device__ __forceinline__ void lru_block_phase(const bf16_t* XR, const bf16_t* GATE, bf16_t* YP, u32x4* HSF, const bf16_t* bdw_j, const float* ga_b, const float* gx_b, const float* lam,
;                                                 LAS unsigned char* lds, int lane, int wave, int G) {
;     ...
;     for (int item = opaque_bid(); item < NB * 32; item += G) {
;         const int b = item >> 5, n2 = item & 31, ch = n2 * 32 + (lane & 31);
;         { const float bias_r = ga_b[ch], bias_i = gx_b[ch], sp = log1pf(__expf(-lam[ch]));
;           lru_dir<0>(XR, GATE, YP, HSF, bdw_j, bias_r, bias_i, sp, b, n2, lane, wave, xl); }
;         __syncthreads();
;         { const float bias_r = ga_b[DM + ch], bias_i = gx_b[DM + ch], sp = log1pf(__expf(-lam[DM + ch]));
;           lru_dir<1>(XR, GATE, YP, HSF, bdw_j + 2 * 16 * 4096, bias_r, bias_i, sp, b, n2, lane, wave, xl); }
.LBB0_11:
	v_readlane_b32 s2, v253, 2
	v_readlane_b32 s3, v253, 3
	s_movk_i32 s76, 0x2000
	v_writelane_b32 v254, s2, 41
	s_mov_b64 s[26:27], 0
	s_mov_b64 s[52:53], 0
	v_writelane_b32 v254, s3, 42
	s_ashr_i32 s3, s70, 31
	s_mov_b32 s2, s70
	v_writelane_b32 v254, s2, 43
	s_nop 1
	v_writelane_b32 v254, s3, 44
	s_lshl_b64 s[2:3], s[2:3], 4
	s_getpc_b64 s[6:7]
	s_add_u32 s6, s6, _ZL4PROG@rel32@lo+4
	s_addc_u32 s7, s7, _ZL4PROG@rel32@hi+12
	s_add_u32 s2, s6, s2
	s_addc_u32 s3, s7, s3
	s_load_dwordx4 s[60:63], s[2:3], 0x0
	s_mov_b64 s[2:3], -1
	v_readlane_b32 s70, v254, 20
	s_waitcnt lgkmcnt(0)
	s_cmp_lt_i32 s60, 4
	s_cbranch_scc1 .LBB0_294
	s_cmp_gt_i32 s60, 5
	s_cbranch_scc0 .LBB0_84
	s_cmp_gt_i32 s60, 6
	s_cbranch_scc0 .LBB0_70
	s_cmp_gt_i32 s60, 7
	s_cbranch_scc0 .LBB0_67
	s_cmp_eq_u32 s60, 8
	s_mov_b64 s[52:53], -1
	s_cbranch_scc0 .LBB0_66
	s_mov_b32 s77, s57
	s_mov_b32 s79, s71
	v_mov_b32 v0, v220
	s_mov_b32 s2, s54
	s_mov_b32 s12, s54
	s_and_b32 s25, s12, 7
	s_lshl_b32 s25, s25, 5
	s_lshr_b32 s12, s12, 3
	s_or_b32 s12, s12, s25
	s_cmpk_gt_i32 s12, 0xff
	v_readfirstlane_b32 s25, v0
	s_cbranch_scc1 .LBB0_65
	v_bfe_u32 v7, v0, 2, 4
	v_and_b32_e32 v172, 31, v0
	v_and_b32_e32 v2, 8, v7
	v_cmp_eq_u32_e32 vcc, v2, v172
	v_mov_b32_e32 v24, 0x3f80
	v_or_b32_e32 v9, 16, v2
	v_readlane_b32 s28, v254, 41
	v_cndmask_b32_e32 v8, 0, v24, vcc
	v_cmp_eq_u32_e32 vcc, v9, v172
	v_or_b32_e32 v11, 1, v2
	v_readlane_b32 s29, v254, 42
	v_cndmask_b32_e32 v9, 0, v24, vcc
	v_or_b32_e32 v10, 2, v2
	v_cmp_eq_u32_e32 vcc, v11, v172
	s_load_dwordx2 s[2:3], s[28:29], 0xd8
	v_or_b32_e32 v13, 17, v2
	v_cndmask_b32_e32 v11, 0, v24, vcc
	v_cmp_eq_u32_e32 vcc, v10, v172
	v_or_b32_e32 v12, 18, v2
	v_or_b32_e32 v15, 3, v2
	v_cndmask_b32_e32 v10, 0, v24, vcc
	v_cmp_eq_u32_e32 vcc, v13, v172
	v_or_b32_e32 v14, 4, v2
	s_ashr_i32 s13, s25, 6
	v_cndmask_b32_e32 v13, 0, v24, vcc
	v_cmp_eq_u32_e32 vcc, v12, v172
	v_or_b32_e32 v17, 19, v2
	s_waitcnt lgkmcnt(0)
	s_add_u32 s64, s2, 0x7600000
	v_cndmask_b32_e32 v12, 0, v24, vcc
	v_cmp_eq_u32_e32 vcc, v15, v172
	v_or_b32_e32 v16, 20, v2
	s_addc_u32 s65, s3, 0
	v_cndmask_b32_e32 v15, 0, v24, vcc
	v_cmp_eq_u32_e32 vcc, v14, v172
	s_ashr_i32 s18, s61, 1
	v_or_b32_e32 v18, 6, v2
	v_cndmask_b32_e32 v14, 0, v24, vcc
	v_cmp_eq_u32_e32 vcc, v17, v172
	s_add_u32 s16, s2, 0x14200000
	v_or_b32_e32 v19, 5, v2
	v_cndmask_b32_e32 v17, 0, v24, vcc
	v_cmp_eq_u32_e32 vcc, v16, v172
	s_addc_u32 s17, s3, 0
	s_ashr_i32 s19, s18, 31
	v_cndmask_b32_e32 v16, 0, v24, vcc
	v_cmp_eq_u32_e32 vcc, v18, v172
	v_or_b32_e32 v20, 22, v2
	s_load_dwordx2 s[6:7], s[28:29], 0x88
	v_cndmask_b32_e32 v18, 0, v24, vcc
	v_cmp_eq_u32_e32 vcc, v19, v172
	s_lshl_b64 s[8:9], s[18:19], 19
	v_or_b32_e32 v21, 21, v2
	v_cndmask_b32_e32 v19, 0, v24, vcc
	v_cmp_eq_u32_e32 vcc, v20, v172
	s_add_u32 s23, s2, s8
	v_or_b32_e32 v22, 7, v7
	v_cndmask_b32_e32 v20, 0, v24, vcc
	v_cmp_eq_u32_e32 vcc, v21, v172
	s_addc_u32 s24, s3, s9
	v_and_b32_e32 v1, 63, v0
	v_cndmask_b32_e32 v21, 0, v24, vcc
	v_cmp_eq_u32_e32 vcc, v22, v172
	v_or_b32_e32 v7, 23, v7
	s_add_u32 s20, s23, 0x900000
	v_cndmask_b32_e32 v22, 0, v24, vcc
	v_cmp_eq_u32_e32 vcc, v7, v172
	v_cmp_gt_u32_e64 s[40:41], 32, v1
	v_lshlrev_b32_e32 v178, 5, v1
	v_bfe_u32 v1, v0, 5, 1
	s_addc_u32 s21, s24, 0
	s_lshl_b64 s[18:19], s[18:19], 13
	v_lshlrev_b32_e32 v3, 2, v0
	v_and_b32_e32 v4, 3, v0
	v_lshrrev_b32_e32 v5, 1, v0
	v_cndmask_b32_e32 v7, 0, v24, vcc
	v_cmp_lt_i32_e32 vcc, v226, v227
	v_lshlrev_b32_e32 v0, 3, v1
	s_load_dwordx4 s[8:11], s[28:29], 0x98
	s_waitcnt lgkmcnt(0)
	s_add_u32 s66, s6, s18
	v_and_or_b32 v23, v5, 12, v4
	v_cndmask_b32_e32 v4, v222, v226, vcc
	s_mov_b32 s6, 0x5040100
	v_cmp_eq_u32_e32 vcc, v0, v172
	v_or_b32_e32 v5, 16, v0
	v_lshlrev_b32_e32 v176, 2, v4
	v_perm_b32 v50, v11, v8, s6
	v_cndmask_b32_e32 v4, 0, v24, vcc
	v_cmp_eq_u32_e32 vcc, v5, v172
	v_or_b32_e32 v8, 1, v0
	v_perm_b32 v57, v7, v20, s6
	v_cndmask_b32_e32 v5, 0, v24, vcc
	v_or_b32_e32 v7, 2, v0
	v_cmp_eq_u32_e32 vcc, v8, v172
	v_perm_b32 v51, v15, v10, s6
	v_or_b32_e32 v10, 17, v0
	v_cndmask_b32_e32 v8, 0, v24, vcc
	v_cmp_eq_u32_e32 vcc, v7, v172
	v_perm_b32 v54, v13, v9, s6
	v_or_b32_e32 v9, 18, v0
	v_cndmask_b32_e32 v7, 0, v24, vcc
	v_cmp_eq_u32_e32 vcc, v10, v172
	s_addc_u32 s67, s7, s19
	v_perm_b32 v55, v17, v12, s6
	v_cndmask_b32_e32 v10, 0, v24, vcc
	v_cmp_eq_u32_e32 vcc, v9, v172
	v_or_b32_e32 v12, 3, v0
	s_add_u32 s68, s8, s18
	v_cndmask_b32_e32 v9, 0, v24, vcc
	v_or_b32_e32 v11, 4, v0
	v_cmp_eq_u32_e32 vcc, v12, v172
	s_addc_u32 s69, s9, s19
	v_perm_b32 v52, v19, v14, s6
	v_cndmask_b32_e32 v12, 0, v24, vcc
	v_cmp_eq_u32_e32 vcc, v11, v172
	v_or_b32_e32 v14, 19, v0
	s_add_u32 s70, s10, s18
	v_cndmask_b32_e32 v11, 0, v24, vcc
	v_or_b32_e32 v13, 20, v0
	v_cmp_eq_u32_e32 vcc, v14, v172
	s_addc_u32 s71, s11, s19
	s_lshl_b32 s22, s13, 1
	v_cndmask_b32_e32 v14, 0, v24, vcc
	v_cmp_eq_u32_e32 vcc, v13, v172
	v_or_b32_e32 v15, 6, v0
	v_perm_b32 v56, v21, v16, s6
	s_cmp_eq_u32 s13, 1
	v_cndmask_b32_e32 v13, 0, v24, vcc
	v_or_b32_e32 v16, 5, v0
	v_cmp_eq_u32_e32 vcc, v15, v172
	s_cselect_b64 s[42:43], -1, 0
	s_cmp_eq_u32 s13, 2
	v_cndmask_b32_e32 v15, 0, v24, vcc
	v_cmp_eq_u32_e32 vcc, v16, v172
	v_or_b32_e32 v17, 22, v0
	v_perm_b32 v53, v22, v18, s6
	s_cselect_b64 s[44:45], -1, 0
	s_cmp_eq_u32 s13, 3
	v_cndmask_b32_e32 v16, 0, v24, vcc
	v_or_b32_e32 v18, 21, v0
	v_cmp_eq_u32_e32 vcc, v17, v172
	s_cselect_b64 s[46:47], -1, 0
	s_cmp_eq_u32 s13, 4
	v_cndmask_b32_e32 v17, 0, v24, vcc
	v_cmp_eq_u32_e32 vcc, v18, v172
	v_or_b32_e32 v19, 7, v0
	s_cselect_b64 s[48:49], -1, 0
	s_cmp_eq_u32 s13, 5
	v_cndmask_b32_e32 v18, 0, v24, vcc
	v_cmp_eq_u32_e32 vcc, v19, v172
	v_or_b32_e32 v20, 23, v0
	s_cselect_b64 s[50:51], -1, 0
	s_cmp_eq_u32 s13, 6
	v_cndmask_b32_e32 v19, 0, v24, vcc
	v_cmp_eq_u32_e32 vcc, v20, v172
	s_cselect_b64 s[52:53], -1, 0
	s_cmp_eq_u32 s13, 7
	v_cndmask_b32_e32 v20, 0, v24, vcc
	v_lshlrev_b32_e32 v102, 4, v1
	v_mov_b32_e32 v103, v49
	s_cselect_b64 s[54:55], -1, 0
	s_add_u32 s23, s23, 0x940000
	v_perm_b32 v60, v16, v11, s6
	v_perm_b32 v59, v12, v7, s6
	v_perm_b32 v61, v19, v15, s6
	v_perm_b32 v58, v8, v4, s6
	v_perm_b32 v64, v18, v13, s6
	v_perm_b32 v63, v14, v9, s6
	v_perm_b32 v65, v20, v17, s6
	v_perm_b32 v62, v10, v5, s6
	v_lshl_add_u64 v[4:5], s[2:3], 0, v[102:103]
	s_mov_b64 s[6:7], 0xba00000
	v_lshlrev_b32_e32 v48, 1, v172
	v_lshlrev_b32_e32 v6, 6, v172
	v_and_b32_e32 v3, 16, v3
	s_addc_u32 s24, s24, 0
	v_lshl_add_u64 v[104:105], v[4:5], 0, s[6:7]
	v_lshl_add_u64 v[4:5], s[2:3], 0, v[48:49]
	s_mov_b64 s[2:3], 0x18600000
	s_andn2_b32 s25, s25, 63
	v_or_b32_e32 v173, v23, v3
	v_lshl_add_u32 v177, v172, 3, 0
	v_lshl_add_u64 v[106:107], v[4:5], 0, s[2:3]
	v_or3_b32 v103, s25, v3, v23
	s_sub_i32 s28, 0, s22
	v_lshlrev_b32_e32 v179, 1, v6
	v_lshlrev_b32_e32 v108, 1, v2
	v_lshlrev_b32_e32 v110, 1, v0
	s_branch .LBB0_19
